# norm_mod(0) modulation prologue: four serial 18-load rounds software-pipelined (each slot's next-round load re-issued right after consumption, ~16 loads kept in flight)
# speedup vs baseline: 1.0045x; 1.0025x over previous
.LBB0_101:
	s_waitcnt vmcnt(4)
	v_min_i32_e32 v24, v144, v177
	v_add_u32_e32 v26, 0xffffe000, v24
	v_ashrrev_i32_e32 v25, 31, v24
	v_cmp_gt_i32_e32 vcc, s12, v24
	v_mov_b32_e32 v28, s39
	v_mov_b32_e32 v29, s37
	v_cndmask_b32_e32 v25, 0, v25, vcc
	v_cndmask_b32_e32 v24, v26, v24, vcc
	v_mov_b32_e32 v30, s38
	v_mov_b32_e32 v31, s36
	v_cndmask_b32_e32 v27, v28, v29, vcc
	v_cndmask_b32_e32 v26, v30, v31, vcc
	v_lshlrev_b64 v[24:25], 12, v[24:25]
	v_lshl_add_u64 v[24:25], v[26:27], 0, v[24:25]
	v_lshl_add_u64 v[24:25], v[24:25], 0, v[146:147]
	v_add_u32_e32 v170, 1, v144
	global_load_dwordx4 v[140:143], v[24:25], off nt
	global_load_dwordx4 v[136:139], v[24:25], off offset:1024 nt
	global_load_dwordx4 v[132:135], v[24:25], off offset:2048 nt
	global_load_dwordx4 v[128:131], v[24:25], off offset:3072 nt
	v_min_i32_e32 v24, v170, v177
	v_ashrrev_i32_e32 v25, 31, v24
	v_add_u32_e32 v26, 0xffffe000, v24
	v_cmp_gt_i32_e32 vcc, s12, v24
	v_add_u32_e32 v168, 2, v144
	v_add_u32_e32 v166, 3, v144
	v_cndmask_b32_e32 v25, 0, v25, vcc
	v_cndmask_b32_e32 v24, v26, v24, vcc
	v_cndmask_b32_e32 v27, v28, v29, vcc
	v_cndmask_b32_e32 v26, v30, v31, vcc
	v_lshlrev_b64 v[24:25], 12, v[24:25]
	v_lshl_add_u64 v[24:25], v[26:27], 0, v[24:25]
	v_lshl_add_u64 v[24:25], v[24:25], 0, v[146:147]
	global_load_dwordx4 v[124:127], v[24:25], off nt
	global_load_dwordx4 v[120:123], v[24:25], off offset:1024 nt
	global_load_dwordx4 v[116:119], v[24:25], off offset:2048 nt
	global_load_dwordx4 v[112:115], v[24:25], off offset:3072 nt
	v_min_i32_e32 v24, v168, v177
	v_ashrrev_i32_e32 v25, 31, v24
	v_add_u32_e32 v26, 0xffffe000, v24
	v_cmp_gt_i32_e32 vcc, s12, v24
	v_add_u32_e32 v164, 4, v144
	v_add_u32_e32 v162, 5, v144
	v_cndmask_b32_e32 v25, 0, v25, vcc
	v_cndmask_b32_e32 v24, v26, v24, vcc
	v_cndmask_b32_e32 v27, v28, v29, vcc
	v_cndmask_b32_e32 v26, v30, v31, vcc
	v_lshlrev_b64 v[24:25], 12, v[24:25]
	v_lshl_add_u64 v[24:25], v[26:27], 0, v[24:25]
	v_lshl_add_u64 v[24:25], v[24:25], 0, v[146:147]
	global_load_dwordx4 v[108:111], v[24:25], off nt
	global_load_dwordx4 v[104:107], v[24:25], off offset:1024 nt
	global_load_dwordx4 v[100:103], v[24:25], off offset:2048 nt
	global_load_dwordx4 v[96:99], v[24:25], off offset:3072 nt
	v_min_i32_e32 v24, v166, v177
	v_ashrrev_i32_e32 v25, 31, v24
	v_add_u32_e32 v26, 0xffffe000, v24
	v_cmp_gt_i32_e32 vcc, s12, v24
	v_add_u32_e32 v145, 0xffffe000, v144
	v_ashrrev_i32_e32 v145, 10, v145
	v_cndmask_b32_e32 v25, 0, v25, vcc
	v_cndmask_b32_e32 v24, v26, v24, vcc
	v_cndmask_b32_e32 v27, v28, v29, vcc
	v_cndmask_b32_e32 v26, v30, v31, vcc
	v_lshlrev_b64 v[24:25], 12, v[24:25]
	v_lshl_add_u64 v[24:25], v[26:27], 0, v[24:25]
	v_lshl_add_u64 v[24:25], v[24:25], 0, v[146:147]
	global_load_dwordx4 v[84:87], v[24:25], off nt
	global_load_dwordx4 v[80:83], v[24:25], off offset:1024 nt
	global_load_dwordx4 v[76:79], v[24:25], off offset:2048 nt
	global_load_dwordx4 v[72:75], v[24:25], off offset:3072 nt
	v_min_i32_e32 v24, v164, v177
	v_ashrrev_i32_e32 v25, 31, v24
	v_add_u32_e32 v26, 0xffffe000, v24
	v_cmp_gt_i32_e32 vcc, s12, v24
	v_add_u32_e32 v145, 1, v145
	s_nop 0
	v_cndmask_b32_e32 v25, 0, v25, vcc
	v_cndmask_b32_e32 v24, v26, v24, vcc
	v_cndmask_b32_e32 v27, v28, v29, vcc
	v_cndmask_b32_e32 v26, v30, v31, vcc
	v_lshlrev_b64 v[24:25], 12, v[24:25]
	v_lshl_add_u64 v[24:25], v[26:27], 0, v[24:25]
	v_min_i32_e32 v26, v162, v177
	v_ashrrev_i32_e32 v27, 31, v26
	v_add_u32_e32 v32, 0xffffe000, v26
	v_cmp_gt_i32_e32 vcc, s12, v26
	v_lshl_add_u64 v[24:25], v[24:25], 0, v[146:147]
	s_nop 0
	v_cndmask_b32_e32 v27, 0, v27, vcc
	v_cndmask_b32_e32 v26, v32, v26, vcc
	v_cndmask_b32_e32 v29, v28, v29, vcc
	v_cndmask_b32_e32 v28, v30, v31, vcc
	v_lshlrev_b64 v[26:27], 12, v[26:27]
	v_lshl_add_u64 v[26:27], v[28:29], 0, v[26:27]
	v_lshl_add_u64 v[26:27], v[26:27], 0, v[146:147]
	global_load_dwordx4 v[60:63], v[24:25], off nt
	global_load_dwordx4 v[56:59], v[24:25], off offset:1024 nt
	global_load_dwordx4 v[52:55], v[24:25], off offset:2048 nt
	global_load_dwordx4 v[48:51], v[24:25], off offset:3072 nt
	global_load_dwordx4 v[36:39], v[26:27], off nt
	global_load_dwordx4 v[32:35], v[26:27], off offset:1024 nt
	global_load_dwordx4 v[28:31], v[26:27], off offset:2048 nt
	s_nop 0
	global_load_dwordx4 v[24:27], v[26:27], off offset:3072 nt
	v_cmp_lt_i32_e32 vcc, s13, v144
	s_nop 1
	v_cndmask_b32_e32 v145, 0, v145, vcc
	v_cmp_ne_u32_e32 vcc, v145, v185
	s_and_saveexec_b64 s[6:7], vcc
	s_cbranch_execz .LBB0_111
	v_mad_i64_i32 v[172:173], s[8:9], v145, s3, v[160:161]
	global_load_dwordx4 v[16:19], v[150:151], off
	global_load_dwordx4 v[20:23], v[152:153], off
	v_add_co_u32_e32 v222, vcc, 0x1410000, v172
	s_nop 1
	v_addc_co_u32_e32 v223, vcc, 0, v173, vcc
	global_load_dwordx4 v[186:189], v[222:223], off
	v_add_co_u32_e32 v222, vcc, 0x1000, v222
	s_nop 1
	v_addc_co_u32_e32 v223, vcc, 0, v223, vcc
	global_load_dwordx4 v[190:193], v[222:223], off
	v_add_co_u32_e32 v222, vcc, 0x1d000, v222
	s_nop 1
	v_addc_co_u32_e32 v223, vcc, 0, v223, vcc
	global_load_dwordx4 v[194:197], v[222:223], off
	v_add_co_u32_e32 v222, vcc, 0x1000, v222
	s_nop 1
	v_addc_co_u32_e32 v223, vcc, 0, v223, vcc
	global_load_dwordx4 v[198:201], v[222:223], off
	v_add_co_u32_e32 v222, vcc, 0x1d000, v222
	s_nop 1
	v_addc_co_u32_e32 v223, vcc, 0, v223, vcc
	global_load_dwordx4 v[202:205], v[222:223], off
	v_add_co_u32_e32 v222, vcc, 0x1000, v222
	s_nop 1
	v_addc_co_u32_e32 v223, vcc, 0, v223, vcc
	global_load_dwordx4 v[206:209], v[222:223], off
	v_add_co_u32_e32 v222, vcc, 0x1d000, v222
	s_nop 1
	v_addc_co_u32_e32 v223, vcc, 0, v223, vcc
	global_load_dwordx4 v[210:213], v[222:223], off
	v_add_co_u32_e32 v222, vcc, 0x1000, v222
	s_nop 1
	v_addc_co_u32_e32 v223, vcc, 0, v223, vcc
	global_load_dwordx4 v[214:217], v[222:223], off
	v_add_co_u32_e32 v222, vcc, 0x1d000, v222
	s_nop 1
	v_addc_co_u32_e32 v223, vcc, 0, v223, vcc
	global_load_dwordx4 v[218:221], v[222:223], off
	v_add_co_u32_e32 v222, vcc, 0x1000, v222
	s_nop 1
	v_addc_co_u32_e32 v223, vcc, 0, v223, vcc
	global_load_dwordx4 v[226:229], v[222:223], off
	v_add_co_u32_e32 v222, vcc, 0x1d000, v222
	s_nop 1
	v_addc_co_u32_e32 v223, vcc, 0, v223, vcc
	global_load_dwordx4 v[230:233], v[222:223], off
	v_add_co_u32_e32 v222, vcc, 0x1000, v222
	s_nop 1
	v_addc_co_u32_e32 v223, vcc, 0, v223, vcc
	global_load_dwordx4 v[234:237], v[222:223], off
	v_add_co_u32_e32 v222, vcc, 0x1d000, v222
	s_nop 1
	v_addc_co_u32_e32 v223, vcc, 0, v223, vcc
	global_load_dwordx4 v[238:241], v[222:223], off
	v_add_co_u32_e32 v222, vcc, 0x1000, v222
	s_nop 1
	v_addc_co_u32_e32 v223, vcc, 0, v223, vcc
	global_load_dwordx4 v[242:245], v[222:223], off
	v_add_co_u32_e32 v222, vcc, 0x1d000, v222
	s_nop 1
	v_addc_co_u32_e32 v223, vcc, 0, v223, vcc
	global_load_dwordx4 v[246:249], v[222:223], off
	v_add_co_u32_e32 v222, vcc, 0x1000, v222
	s_nop 1
	v_addc_co_u32_e32 v223, vcc, 0, v223, vcc
	global_load_dwordx4 v[250:253], v[222:223], off
	s_waitcnt vmcnt(15)
	v_pk_add_f32 v[18:19], v[18:19], v[188:189]
	v_pk_add_f32 v[16:17], v[16:17], v[186:187]
	global_load_dwordx4 v[40:43], v[150:151], off offset:1024
	global_load_dwordx4 v[44:47], v[154:155], off
	v_add_co_u32_e32 v222, vcc, 0x1410000, v172
	s_nop 1
	v_addc_co_u32_e32 v223, vcc, 0, v173, vcc
	global_load_dwordx4 v[186:189], v[222:223], off offset:1024
	s_waitcnt vmcnt(17)
	v_pk_add_f32 v[22:23], v[22:23], v[192:193]
	v_pk_add_f32 v[20:21], v[20:21], v[190:191]
	v_add_co_u32_e32 v222, vcc, 0x1000, v222
	s_nop 1
	v_addc_co_u32_e32 v223, vcc, 0, v223, vcc
	global_load_dwordx4 v[190:193], v[222:223], off offset:1024
	s_waitcnt vmcnt(17)
	v_pk_add_f32 v[18:19], v[18:19], v[196:197]
	v_pk_add_f32 v[16:17], v[16:17], v[194:195]
	v_add_co_u32_e32 v222, vcc, 0x1d000, v222
	s_nop 1
	v_addc_co_u32_e32 v223, vcc, 0, v223, vcc
	global_load_dwordx4 v[194:197], v[222:223], off offset:1024
	s_waitcnt vmcnt(17)
	v_pk_add_f32 v[22:23], v[22:23], v[200:201]
	v_pk_add_f32 v[20:21], v[20:21], v[198:199]
	v_add_co_u32_e32 v222, vcc, 0x1000, v222
	s_nop 1
	v_addc_co_u32_e32 v223, vcc, 0, v223, vcc
	global_load_dwordx4 v[198:201], v[222:223], off offset:1024
	s_waitcnt vmcnt(17)
	v_pk_add_f32 v[18:19], v[18:19], v[204:205]
	v_pk_add_f32 v[16:17], v[16:17], v[202:203]
	v_add_co_u32_e32 v222, vcc, 0x1d000, v222
	s_nop 1
	v_addc_co_u32_e32 v223, vcc, 0, v223, vcc
	global_load_dwordx4 v[202:205], v[222:223], off offset:1024
	s_waitcnt vmcnt(17)
	v_pk_add_f32 v[22:23], v[22:23], v[208:209]
	v_pk_add_f32 v[20:21], v[20:21], v[206:207]
	v_add_co_u32_e32 v222, vcc, 0x1000, v222
	s_nop 1
	v_addc_co_u32_e32 v223, vcc, 0, v223, vcc
	global_load_dwordx4 v[206:209], v[222:223], off offset:1024
	s_waitcnt vmcnt(17)
	v_pk_add_f32 v[18:19], v[18:19], v[212:213]
	v_pk_add_f32 v[16:17], v[16:17], v[210:211]
	v_add_co_u32_e32 v222, vcc, 0x1d000, v222
	s_nop 1
	v_addc_co_u32_e32 v223, vcc, 0, v223, vcc
	global_load_dwordx4 v[210:213], v[222:223], off offset:1024
	s_waitcnt vmcnt(17)
	v_pk_add_f32 v[22:23], v[22:23], v[216:217]
	v_pk_add_f32 v[20:21], v[20:21], v[214:215]
	v_add_co_u32_e32 v222, vcc, 0x1000, v222
	s_nop 1
	v_addc_co_u32_e32 v223, vcc, 0, v223, vcc
	global_load_dwordx4 v[214:217], v[222:223], off offset:1024
	s_waitcnt vmcnt(17)
	v_pk_add_f32 v[18:19], v[18:19], v[220:221]
	v_pk_add_f32 v[16:17], v[16:17], v[218:219]
	v_add_co_u32_e32 v222, vcc, 0x1d000, v222
	s_nop 1
	v_addc_co_u32_e32 v223, vcc, 0, v223, vcc
	global_load_dwordx4 v[218:221], v[222:223], off offset:1024
	s_waitcnt vmcnt(17)
	v_pk_add_f32 v[22:23], v[22:23], v[228:229]
	v_pk_add_f32 v[20:21], v[20:21], v[226:227]
	v_add_co_u32_e32 v222, vcc, 0x1000, v222
	s_nop 1
	v_addc_co_u32_e32 v223, vcc, 0, v223, vcc
	global_load_dwordx4 v[226:229], v[222:223], off offset:1024
	s_waitcnt vmcnt(17)
	v_pk_add_f32 v[18:19], v[18:19], v[232:233]
	v_pk_add_f32 v[16:17], v[16:17], v[230:231]
	v_add_co_u32_e32 v222, vcc, 0x1d000, v222
	s_nop 1
	v_addc_co_u32_e32 v223, vcc, 0, v223, vcc
	global_load_dwordx4 v[230:233], v[222:223], off offset:1024
	s_waitcnt vmcnt(17)
	v_pk_add_f32 v[22:23], v[22:23], v[236:237]
	v_pk_add_f32 v[20:21], v[20:21], v[234:235]
	v_add_co_u32_e32 v222, vcc, 0x1000, v222
	s_nop 1
	v_addc_co_u32_e32 v223, vcc, 0, v223, vcc
	global_load_dwordx4 v[234:237], v[222:223], off offset:1024
	s_waitcnt vmcnt(17)
	v_pk_add_f32 v[18:19], v[18:19], v[240:241]
	v_pk_add_f32 v[16:17], v[16:17], v[238:239]
	v_add_co_u32_e32 v222, vcc, 0x1d000, v222
	s_nop 1
	v_addc_co_u32_e32 v223, vcc, 0, v223, vcc
	global_load_dwordx4 v[238:241], v[222:223], off offset:1024
	s_waitcnt vmcnt(17)
	v_pk_add_f32 v[22:23], v[22:23], v[244:245]
	v_pk_add_f32 v[20:21], v[20:21], v[242:243]
	v_add_co_u32_e32 v222, vcc, 0x1000, v222
	s_nop 1
	v_addc_co_u32_e32 v223, vcc, 0, v223, vcc
	global_load_dwordx4 v[242:245], v[222:223], off offset:1024
	s_waitcnt vmcnt(17)
	v_pk_add_f32 v[18:19], v[18:19], v[248:249]
	v_pk_add_f32 v[16:17], v[16:17], v[246:247]
	v_add_co_u32_e32 v222, vcc, 0x1d000, v222
	s_nop 1
	v_addc_co_u32_e32 v223, vcc, 0, v223, vcc
	global_load_dwordx4 v[246:249], v[222:223], off offset:1024
	s_waitcnt vmcnt(17)
	v_pk_add_f32 v[22:23], v[22:23], v[252:253]
	v_pk_add_f32 v[20:21], v[20:21], v[250:251]
	v_add_co_u32_e32 v222, vcc, 0x1000, v222
	s_nop 1
	v_addc_co_u32_e32 v223, vcc, 0, v223, vcc
	global_load_dwordx4 v[250:253], v[222:223], off offset:1024
	s_waitcnt vmcnt(15)
	v_pk_add_f32 v[42:43], v[42:43], v[188:189]
	v_pk_add_f32 v[40:41], v[40:41], v[186:187]
	global_load_dwordx4 v[64:67], v[150:151], off offset:2048
	global_load_dwordx4 v[68:71], v[156:157], off
	v_add_co_u32_e32 v222, vcc, 0x1410000, v172
	s_nop 1
	v_addc_co_u32_e32 v223, vcc, 0, v173, vcc
	global_load_dwordx4 v[186:189], v[222:223], off offset:2048
	s_waitcnt vmcnt(17)
	v_pk_add_f32 v[46:47], v[46:47], v[192:193]
	v_pk_add_f32 v[44:45], v[44:45], v[190:191]
	v_add_co_u32_e32 v222, vcc, 0x1000, v222
	s_nop 1
	v_addc_co_u32_e32 v223, vcc, 0, v223, vcc
	global_load_dwordx4 v[190:193], v[222:223], off offset:2048
	s_waitcnt vmcnt(17)
	v_pk_add_f32 v[42:43], v[42:43], v[196:197]
	v_pk_add_f32 v[40:41], v[40:41], v[194:195]
	v_add_co_u32_e32 v222, vcc, 0x1d000, v222
	s_nop 1
	v_addc_co_u32_e32 v223, vcc, 0, v223, vcc
	global_load_dwordx4 v[194:197], v[222:223], off offset:2048
	s_waitcnt vmcnt(17)
	v_pk_add_f32 v[46:47], v[46:47], v[200:201]
	v_pk_add_f32 v[44:45], v[44:45], v[198:199]
	v_add_co_u32_e32 v222, vcc, 0x1000, v222
	s_nop 1
	v_addc_co_u32_e32 v223, vcc, 0, v223, vcc
	global_load_dwordx4 v[198:201], v[222:223], off offset:2048
	s_waitcnt vmcnt(17)
	v_pk_add_f32 v[42:43], v[42:43], v[204:205]
	v_pk_add_f32 v[40:41], v[40:41], v[202:203]
	v_add_co_u32_e32 v222, vcc, 0x1d000, v222
	s_nop 1
	v_addc_co_u32_e32 v223, vcc, 0, v223, vcc
	global_load_dwordx4 v[202:205], v[222:223], off offset:2048
	s_waitcnt vmcnt(17)
	v_pk_add_f32 v[46:47], v[46:47], v[208:209]
	v_pk_add_f32 v[44:45], v[44:45], v[206:207]
	v_add_co_u32_e32 v222, vcc, 0x1000, v222
	s_nop 1
	v_addc_co_u32_e32 v223, vcc, 0, v223, vcc
	global_load_dwordx4 v[206:209], v[222:223], off offset:2048
	s_waitcnt vmcnt(17)
	v_pk_add_f32 v[42:43], v[42:43], v[212:213]
	v_pk_add_f32 v[40:41], v[40:41], v[210:211]
	v_add_co_u32_e32 v222, vcc, 0x1d000, v222
	s_nop 1
	v_addc_co_u32_e32 v223, vcc, 0, v223, vcc
	global_load_dwordx4 v[210:213], v[222:223], off offset:2048
	s_waitcnt vmcnt(17)
	v_pk_add_f32 v[46:47], v[46:47], v[216:217]
	v_pk_add_f32 v[44:45], v[44:45], v[214:215]
	v_add_co_u32_e32 v222, vcc, 0x1000, v222
	s_nop 1
	v_addc_co_u32_e32 v223, vcc, 0, v223, vcc
	global_load_dwordx4 v[214:217], v[222:223], off offset:2048
	s_waitcnt vmcnt(17)
	v_pk_add_f32 v[42:43], v[42:43], v[220:221]
	v_pk_add_f32 v[40:41], v[40:41], v[218:219]
	v_add_co_u32_e32 v222, vcc, 0x1d000, v222
	s_nop 1
	v_addc_co_u32_e32 v223, vcc, 0, v223, vcc
	global_load_dwordx4 v[218:221], v[222:223], off offset:2048
	s_waitcnt vmcnt(17)
	v_pk_add_f32 v[46:47], v[46:47], v[228:229]
	v_pk_add_f32 v[44:45], v[44:45], v[226:227]
	v_add_co_u32_e32 v222, vcc, 0x1000, v222
	s_nop 1
	v_addc_co_u32_e32 v223, vcc, 0, v223, vcc
	global_load_dwordx4 v[226:229], v[222:223], off offset:2048
	s_waitcnt vmcnt(17)
	v_pk_add_f32 v[42:43], v[42:43], v[232:233]
	v_pk_add_f32 v[40:41], v[40:41], v[230:231]
	v_add_co_u32_e32 v222, vcc, 0x1d000, v222
	s_nop 1
	v_addc_co_u32_e32 v223, vcc, 0, v223, vcc
	global_load_dwordx4 v[230:233], v[222:223], off offset:2048
	s_waitcnt vmcnt(17)
	v_pk_add_f32 v[46:47], v[46:47], v[236:237]
	v_pk_add_f32 v[44:45], v[44:45], v[234:235]
	v_add_co_u32_e32 v222, vcc, 0x1000, v222
	s_nop 1
	v_addc_co_u32_e32 v223, vcc, 0, v223, vcc
	global_load_dwordx4 v[234:237], v[222:223], off offset:2048
	s_waitcnt vmcnt(17)
	v_pk_add_f32 v[42:43], v[42:43], v[240:241]
	v_pk_add_f32 v[40:41], v[40:41], v[238:239]
	v_add_co_u32_e32 v222, vcc, 0x1d000, v222
	s_nop 1
	v_addc_co_u32_e32 v223, vcc, 0, v223, vcc
	global_load_dwordx4 v[238:241], v[222:223], off offset:2048
	s_waitcnt vmcnt(17)
	v_pk_add_f32 v[46:47], v[46:47], v[244:245]
	v_pk_add_f32 v[44:45], v[44:45], v[242:243]
	v_add_co_u32_e32 v222, vcc, 0x1000, v222
	s_nop 1
	v_addc_co_u32_e32 v223, vcc, 0, v223, vcc
	global_load_dwordx4 v[242:245], v[222:223], off offset:2048
	s_waitcnt vmcnt(17)
	v_pk_add_f32 v[42:43], v[42:43], v[248:249]
	v_pk_add_f32 v[40:41], v[40:41], v[246:247]
	v_add_co_u32_e32 v222, vcc, 0x1d000, v222
	s_nop 1
	v_addc_co_u32_e32 v223, vcc, 0, v223, vcc
	global_load_dwordx4 v[246:249], v[222:223], off offset:2048
	s_waitcnt vmcnt(17)
	v_pk_add_f32 v[46:47], v[46:47], v[252:253]
	v_pk_add_f32 v[44:45], v[44:45], v[250:251]
	v_add_co_u32_e32 v222, vcc, 0x1000, v222
	s_nop 1
	v_addc_co_u32_e32 v223, vcc, 0, v223, vcc
	global_load_dwordx4 v[250:253], v[222:223], off offset:2048
	s_waitcnt vmcnt(15)
	v_pk_add_f32 v[66:67], v[66:67], v[188:189]
	v_pk_add_f32 v[64:65], v[64:65], v[186:187]
	global_load_dwordx4 v[88:91], v[150:151], off offset:3072
	global_load_dwordx4 v[92:95], v[158:159], off
	v_add_co_u32_e32 v222, vcc, 0x1410000, v172
	s_nop 1
	v_addc_co_u32_e32 v223, vcc, 0, v173, vcc
	global_load_dwordx4 v[186:189], v[222:223], off offset:3072
	s_waitcnt vmcnt(17)
	v_pk_add_f32 v[70:71], v[70:71], v[192:193]
	v_pk_add_f32 v[68:69], v[68:69], v[190:191]
	v_add_co_u32_e32 v222, vcc, 0x1000, v222
	s_nop 1
	v_addc_co_u32_e32 v223, vcc, 0, v223, vcc
	global_load_dwordx4 v[190:193], v[222:223], off offset:3072
	s_waitcnt vmcnt(17)
	v_pk_add_f32 v[66:67], v[66:67], v[196:197]
	v_pk_add_f32 v[64:65], v[64:65], v[194:195]
	v_add_co_u32_e32 v222, vcc, 0x1d000, v222
	s_nop 1
	v_addc_co_u32_e32 v223, vcc, 0, v223, vcc
	global_load_dwordx4 v[194:197], v[222:223], off offset:3072
	s_waitcnt vmcnt(17)
	v_pk_add_f32 v[70:71], v[70:71], v[200:201]
	v_pk_add_f32 v[68:69], v[68:69], v[198:199]
	v_add_co_u32_e32 v222, vcc, 0x1000, v222
	s_nop 1
	v_addc_co_u32_e32 v223, vcc, 0, v223, vcc
	global_load_dwordx4 v[198:201], v[222:223], off offset:3072
	s_waitcnt vmcnt(17)
	v_pk_add_f32 v[66:67], v[66:67], v[204:205]
	v_pk_add_f32 v[64:65], v[64:65], v[202:203]
	v_add_co_u32_e32 v222, vcc, 0x1d000, v222
	s_nop 1
	v_addc_co_u32_e32 v223, vcc, 0, v223, vcc
	global_load_dwordx4 v[202:205], v[222:223], off offset:3072
	s_waitcnt vmcnt(17)
	v_pk_add_f32 v[70:71], v[70:71], v[208:209]
	v_pk_add_f32 v[68:69], v[68:69], v[206:207]
	v_add_co_u32_e32 v222, vcc, 0x1000, v222
	s_nop 1
	v_addc_co_u32_e32 v223, vcc, 0, v223, vcc
	global_load_dwordx4 v[206:209], v[222:223], off offset:3072
	s_waitcnt vmcnt(17)
	v_pk_add_f32 v[66:67], v[66:67], v[212:213]
	v_pk_add_f32 v[64:65], v[64:65], v[210:211]
	v_add_co_u32_e32 v222, vcc, 0x1d000, v222
	s_nop 1
	v_addc_co_u32_e32 v223, vcc, 0, v223, vcc
	global_load_dwordx4 v[210:213], v[222:223], off offset:3072
	s_waitcnt vmcnt(17)
	v_pk_add_f32 v[70:71], v[70:71], v[216:217]
	v_pk_add_f32 v[68:69], v[68:69], v[214:215]
	v_add_co_u32_e32 v222, vcc, 0x1000, v222
	s_nop 1
	v_addc_co_u32_e32 v223, vcc, 0, v223, vcc
	global_load_dwordx4 v[214:217], v[222:223], off offset:3072
	s_waitcnt vmcnt(17)
	v_pk_add_f32 v[66:67], v[66:67], v[220:221]
	v_pk_add_f32 v[64:65], v[64:65], v[218:219]
	v_add_co_u32_e32 v222, vcc, 0x1d000, v222
	s_nop 1
	v_addc_co_u32_e32 v223, vcc, 0, v223, vcc
	global_load_dwordx4 v[218:221], v[222:223], off offset:3072
	s_waitcnt vmcnt(17)
	v_pk_add_f32 v[70:71], v[70:71], v[228:229]
	v_pk_add_f32 v[68:69], v[68:69], v[226:227]
	v_add_co_u32_e32 v222, vcc, 0x1000, v222
	s_nop 1
	v_addc_co_u32_e32 v223, vcc, 0, v223, vcc
	global_load_dwordx4 v[226:229], v[222:223], off offset:3072
	s_waitcnt vmcnt(17)
	v_pk_add_f32 v[66:67], v[66:67], v[232:233]
	v_pk_add_f32 v[64:65], v[64:65], v[230:231]
	v_add_co_u32_e32 v222, vcc, 0x1d000, v222
	s_nop 1
	v_addc_co_u32_e32 v223, vcc, 0, v223, vcc
	global_load_dwordx4 v[230:233], v[222:223], off offset:3072
	s_waitcnt vmcnt(17)
	v_pk_add_f32 v[70:71], v[70:71], v[236:237]
	v_pk_add_f32 v[68:69], v[68:69], v[234:235]
	v_add_co_u32_e32 v222, vcc, 0x1000, v222
	s_nop 1
	v_addc_co_u32_e32 v223, vcc, 0, v223, vcc
	global_load_dwordx4 v[234:237], v[222:223], off offset:3072
	s_waitcnt vmcnt(17)
	v_pk_add_f32 v[66:67], v[66:67], v[240:241]
	v_pk_add_f32 v[64:65], v[64:65], v[238:239]
	v_add_co_u32_e32 v222, vcc, 0x1d000, v222
	s_nop 1
	v_addc_co_u32_e32 v223, vcc, 0, v223, vcc
	global_load_dwordx4 v[238:241], v[222:223], off offset:3072
	s_waitcnt vmcnt(17)
	v_pk_add_f32 v[70:71], v[70:71], v[244:245]
	v_pk_add_f32 v[68:69], v[68:69], v[242:243]
	v_add_co_u32_e32 v222, vcc, 0x1000, v222
	s_nop 1
	v_addc_co_u32_e32 v223, vcc, 0, v223, vcc
	global_load_dwordx4 v[242:245], v[222:223], off offset:3072
	s_waitcnt vmcnt(17)
	v_pk_add_f32 v[66:67], v[66:67], v[248:249]
	v_pk_add_f32 v[64:65], v[64:65], v[246:247]
	v_add_co_u32_e32 v222, vcc, 0x1d000, v222
	s_nop 1
	v_addc_co_u32_e32 v223, vcc, 0, v223, vcc
	global_load_dwordx4 v[246:249], v[222:223], off offset:3072
	s_waitcnt vmcnt(17)
	v_pk_add_f32 v[70:71], v[70:71], v[252:253]
	v_pk_add_f32 v[68:69], v[68:69], v[250:251]
	v_add_co_u32_e32 v222, vcc, 0x1000, v222
	s_nop 1
	v_addc_co_u32_e32 v223, vcc, 0, v223, vcc
	global_load_dwordx4 v[250:253], v[222:223], off offset:3072
	s_waitcnt vmcnt(15)
	v_pk_add_f32 v[90:91], v[90:91], v[188:189]
	v_pk_add_f32 v[88:89], v[88:89], v[186:187]
	s_waitcnt vmcnt(14)
	v_pk_add_f32 v[94:95], v[94:95], v[192:193]
	v_pk_add_f32 v[92:93], v[92:93], v[190:191]
	s_waitcnt vmcnt(13)
	v_pk_add_f32 v[90:91], v[90:91], v[196:197]
	v_pk_add_f32 v[88:89], v[88:89], v[194:195]
	s_waitcnt vmcnt(12)
	v_pk_add_f32 v[94:95], v[94:95], v[200:201]
	v_pk_add_f32 v[92:93], v[92:93], v[198:199]
	s_waitcnt vmcnt(11)
	v_pk_add_f32 v[90:91], v[90:91], v[204:205]
	v_pk_add_f32 v[88:89], v[88:89], v[202:203]
	s_waitcnt vmcnt(10)
	v_pk_add_f32 v[94:95], v[94:95], v[208:209]
	v_pk_add_f32 v[92:93], v[92:93], v[206:207]
	s_waitcnt vmcnt(9)
	v_pk_add_f32 v[90:91], v[90:91], v[212:213]
	v_pk_add_f32 v[88:89], v[88:89], v[210:211]
	s_waitcnt vmcnt(8)
	v_pk_add_f32 v[94:95], v[94:95], v[216:217]
	v_pk_add_f32 v[92:93], v[92:93], v[214:215]
	s_waitcnt vmcnt(7)
	v_pk_add_f32 v[90:91], v[90:91], v[220:221]
	v_pk_add_f32 v[88:89], v[88:89], v[218:219]
	s_waitcnt vmcnt(6)
	v_pk_add_f32 v[94:95], v[94:95], v[228:229]
	v_pk_add_f32 v[92:93], v[92:93], v[226:227]
	s_waitcnt vmcnt(5)
	v_pk_add_f32 v[90:91], v[90:91], v[232:233]
	v_pk_add_f32 v[88:89], v[88:89], v[230:231]
	s_waitcnt vmcnt(4)
	v_pk_add_f32 v[94:95], v[94:95], v[236:237]
	v_pk_add_f32 v[92:93], v[92:93], v[234:235]
	s_waitcnt vmcnt(3)
	v_pk_add_f32 v[90:91], v[90:91], v[240:241]
	v_pk_add_f32 v[88:89], v[88:89], v[238:239]
	s_waitcnt vmcnt(2)
	v_pk_add_f32 v[94:95], v[94:95], v[244:245]
	v_pk_add_f32 v[92:93], v[92:93], v[242:243]
	s_waitcnt vmcnt(1)
	v_pk_add_f32 v[90:91], v[90:91], v[248:249]
	v_pk_add_f32 v[88:89], v[88:89], v[246:247]
	s_waitcnt vmcnt(0)
	v_pk_add_f32 v[94:95], v[94:95], v[252:253]
	v_pk_add_f32 v[92:93], v[92:93], v[250:251]
	v_mov_b32_e32 v185, v145
